# phase-1 row split rebalanced around the 64 fold-GEMM workgroups; ssd paired 32-bit LDS stores; p7/p10/p12 epilogue load hoists
# speedup vs baseline: 1.0027x; 1.0024x over previous
; __device__ __forceinline__ void phase_modulate(const float* src_lat, const float* src_ctx, int nrows, const float* normw, const float* mod, int shidx, int scidx, bf16_t* dst) {
;     const int lane = threadIdx.x & 63, rpb = (nrows + (int)gridDim.x - 1) / (int)gridDim.x, rend = min(nrows, ((int)blockIdx.x + 1) * rpb), gw = blockIdx.x * rpb + (threadIdx.x >> 6), NGW = 8;
;     f32x4 v[8], wsc[8], shv[8]; int cur_mi = -1;
;     if (gw < rend) { const float* xr = (gw < MLAT) ? src_lat + (size_t)gw * DM : src_ctx + (size_t)(gw - MLAT) * DM;
; #pragma unroll
;         for (int j = 0; j < 8; ++j) v[j] = *(const f32x4*)(xr + 4 * (lane + 64 * j)); }
;     for (int row = gw; row < rend; row += NGW) {
;         f32x4 nv[8]; const int nrow = row + NGW;
;         if (nrow < rend) { const float* xr = (nrow < MLAT) ? src_lat + (size_t)nrow * DM : src_ctx + (size_t)(nrow - MLAT) * DM;
; #pragma unroll
;             for (int j = 0; j < 8; ++j) nv[j] = *(const f32x4*)(xr + 4 * (lane + 64 * j)); }
;         const int mi = (row < MLAT) ? (row >> 12) : 4;
;         if (mi != cur_mi) { cur_mi = mi; const float* mr = mod + (size_t)mi * 12288;
; #pragma unroll
;             for (int j = 0; j < 8; ++j) { const int col = 4 * (lane + 64 * j); wsc[j] = *(const f32x4*)(normw + col) * (*(const f32x4*)(mr + scidx * DM + col) + 1.0f); shv[j] = *(const f32x4*)(mr + shidx * DM + col); } }
.LBB0_128:
	s_abs_i32 s0, s70
	v_cvt_f32_u32_e32 v2, s0
	s_sub_i32 s3, 0, s0
	s_add_i32 s1, s70, 0x43ff
	s_xor_b32 s2, s1, s70
	v_rcp_iflag_f32_e32 v2, v2
	s_abs_i32 s1, s1
	s_ashr_i32 s2, s2, 31
	v_lshrrev_b32_e32 v133, 6, v154
	v_mul_f32_e32 v2, 0x4f7ffffe, v2
	v_cvt_u32_f32_e32 v2, v2
	s_nop 0
	v_readfirstlane_b32 s6, v2
	s_mul_i32 s3, s3, s6
	s_mul_hi_u32 s3, s6, s3
	s_add_i32 s6, s6, s3
	s_mul_hi_u32 s3, s1, s6
	s_mul_i32 s6, s3, s0
	s_sub_i32 s1, s1, s6
	s_add_i32 s7, s3, 1
	s_sub_i32 s6, s1, s0
	s_cmp_ge_u32 s1, s0
	s_cselect_b32 s3, s7, s3
	s_cselect_b32 s1, s6, s1
	s_add_i32 s6, s3, 1
	s_cmp_ge_u32 s1, s0
	s_cselect_b32 s0, s6, s3
	s_xor_b32 s0, s0, s2
	s_cmp_lt_i32 s88, 64
	s_cselect_b32 s6, 45, 0x4c
	s_cselect_b32 s7, 0, 0xfffff840
	s_mul_i32 s0, s6, s88
	s_add_i32 s0, s0, s7
	s_add_i32 s1, s0, s6
	s_min_i32 s14, s1, 0x4400
	v_add_u32_e32 v164, s0, v133
	v_cmp_gt_i32_e32 vcc, s14, v164
	s_and_saveexec_b64 s[2:3], vcc
	s_cbranch_execz .LBB0_135
	v_readlane_b32 s16, v235, 5
	v_readlane_b32 s17, v235, 6
	v_readlane_b32 s20, v235, 9
	v_readlane_b32 s21, v235, 10
	s_movk_i32 s0, 0x4000
	s_mov_b64 s[8:9], s[16:17]
	s_mov_b64 s[12:13], s[20:21]
	v_add_u32_e32 v2, 0xffffc000, v164
	v_ashrrev_i32_e32 v165, 31, v164
	v_cmp_gt_i32_e32 vcc, s0, v164
	v_mov_b32_e32 v4, s13
	v_mov_b32_e32 v5, s9
	v_cndmask_b32_e32 v3, 0, v165, vcc
	v_cndmask_b32_e32 v2, v2, v164, vcc
	v_cndmask_b32_e32 v5, v4, v5, vcc
	v_mov_b32_e32 v4, s12
	v_mov_b32_e32 v6, s8
	v_cndmask_b32_e32 v4, v4, v6, vcc
	v_lshlrev_b64 v[2:3], 13, v[2:3]
	v_and_b32_e32 v132, 0xfc, v1
	v_mov_b32_e32 v131, 0
	v_lshl_add_u64 v[2:3], v[4:5], 0, v[2:3]
	v_lshlrev_b32_e32 v130, 2, v132
	v_lshl_add_u64 v[10:11], v[2:3], 0, v[130:131]
	global_load_dwordx4 v[66:69], v[10:11], off
	global_load_dwordx4 v[30:33], v[10:11], off offset:1024
	s_movk_i32 s0, 0x1000
	v_add_co_u32_e32 v12, vcc, s0, v10
	v_mbcnt_lo_u32_b32 v1, -1, 0
	s_nop 0
	v_addc_co_u32_e32 v13, vcc, 0, v11, vcc
	global_load_dwordx4 v[6:9], v[12:13], off offset:2048
	global_load_dwordx4 v[2:5], v[12:13], off offset:3072
	global_load_dwordx4 v[26:29], v[10:11], off offset:2048
	global_load_dwordx4 v[22:25], v[10:11], off offset:3072
	global_load_dwordx4 v[14:17], v[12:13], off
	s_nop 0
	global_load_dwordx4 v[10:13], v[12:13], off offset:1024
	v_mbcnt_hi_u32_b32 v18, -1, v1
	v_and_b32_e32 v1, 64, v18
	v_add_u32_e32 v19, 64, v1
	v_xor_b32_e32 v1, 1, v18
	v_cmp_lt_i32_e32 vcc, v1, v19
	v_xor_b32_e32 v20, 2, v18
	v_readlane_b32 s28, v235, 17
	v_cndmask_b32_e32 v1, v18, v1, vcc
	v_cmp_lt_i32_e32 vcc, v20, v19
	v_readlane_b32 s29, v235, 18
	s_mov_b64 s[20:21], s[28:29]
	v_cndmask_b32_e32 v20, v18, v20, vcc
	v_lshlrev_b32_e32 v155, 2, v20
	v_xor_b32_e32 v20, 4, v18
	v_cmp_lt_i32_e32 vcc, v20, v19
	v_or_b32_e32 v36, 0x400, v132
	v_lshl_add_u64 v[134:135], s[20:21], 0, v[130:131]
	v_cndmask_b32_e32 v20, v18, v20, vcc
	v_lshlrev_b32_e32 v166, 2, v20
	v_xor_b32_e32 v20, 8, v18
	v_cmp_lt_i32_e32 vcc, v20, v19
	v_lshlrev_b32_e32 v130, 2, v36
	v_or_b32_e32 v38, 0x500, v132
	v_cndmask_b32_e32 v20, v18, v20, vcc
	v_lshlrev_b32_e32 v167, 2, v20
	v_xor_b32_e32 v20, 16, v18
	v_cmp_lt_i32_e32 vcc, v20, v19
	v_lshl_add_u64 v[136:137], s[20:21], 0, v[130:131]
	v_lshlrev_b32_e32 v130, 2, v38
	v_cndmask_b32_e32 v20, v18, v20, vcc
	v_lshlrev_b32_e32 v168, 2, v20
	v_xor_b32_e32 v20, 32, v18
	v_cmp_lt_i32_e32 vcc, v20, v19
	v_or_b32_e32 v40, 0x600, v132
	v_lshl_add_u64 v[138:139], s[20:21], 0, v[130:131]
	v_cndmask_b32_e32 v18, v18, v20, vcc
	v_lshlrev_b32_e32 v130, 2, v40
	v_or_b32_e32 v42, 0x700, v132
	v_lshlrev_b64 v[44:45], 12, v[164:165]
	v_and_b32_e32 v19, 63, v154
	v_lshlrev_b32_e32 v169, 2, v18
	v_or_b32_e32 v18, 0x100, v132
	v_or_b32_e32 v20, 0x200, v132
	v_or_b32_e32 v34, 0x300, v132
	v_lshl_add_u64 v[140:141], s[20:21], 0, v[130:131]
	v_lshlrev_b32_e32 v130, 2, v42
	v_lshl_or_b32 v44, v19, 3, v44
	v_mov_b32_e32 v147, -1
	v_lshlrev_b32_e32 v1, 2, v1
	v_lshl_add_u64 v[142:143], s[20:21], 0, v[130:131]
	v_lshl_add_u64 v[144:145], s[82:83], 0, v[44:45]
	s_mov_b64 s[6:7], 0
	s_movk_i32 s15, 0x3ff8
	s_mov_b64 s[8:9], 0x2000
	v_lshlrev_b32_e32 v146, 2, v18
	v_lshlrev_b32_e32 v148, 2, v20
	v_lshlrev_b32_e32 v150, 2, v34
	v_lshlrev_b32_e32 v152, 2, v36
	v_lshlrev_b32_e32 v156, 2, v38
	v_lshlrev_b32_e32 v158, 2, v40
	v_lshlrev_b32_e32 v160, 2, v42
	v_mov_b32_e32 v170, 0x358637bd
	s_mov_b32 s16, 0x800000
	s_mov_b64 s[10:11], 0x8000
	v_readlane_b32 s18, v235, 7
	v_readlane_b32 s19, v235, 8
	v_readlane_b32 s22, v235, 11
	v_readlane_b32 s23, v235, 12
	v_readlane_b32 s24, v235, 13
	v_readlane_b32 s25, v235, 14
	v_readlane_b32 s26, v235, 15
	v_readlane_b32 s27, v235, 16
	v_readlane_b32 s30, v235, 19
	v_readlane_b32 s31, v235, 20
	s_waitcnt vmcnt(0)
	v_mov_b32_e32 v171, v2
	v_mov_b32_e32 v172, v3
	v_mov_b32_e32 v173, v4
	v_mov_b32_e32 v174, v5
	s_branch .LBB0_131
